# phase-0 rmsnorm wave sum: permlane32_swap + DPP row_ror steps (same pairing order), one ds_bpermute left (on v028)
# speedup vs baseline: 1.0004x; 1.0004x over previous
; DI unsigned pack2(float a, float b) { hwf2 v = {a, b}; hwbf2 r = __builtin_convertvector(v, hwbf2); return __builtin_bit_cast(unsigned, r); }
; DI float wave_sum(float v) {
; #pragma unroll
;   for (int o = 32; o >= 1; o >>= 1) v += __shfl_xor(v, o);
;   return v;
; }
; DI void phase0(const Params& p, int l, char* smem) {
;     ...
;     const int tstep = gridDim.x * 4;
;     int t = blockIdx.x * 4 + wave;
;     float4 v0, v1, v2, v3;
;     if (t < T_TOK) { const float4* xr = (const float4*)(x + (size_t)t * 1024); v0 = xr[lane]; v1 = xr[lane + 64]; v2 = xr[lane + 128]; v3 = xr[lane + 192]; }
; #pragma unroll 1
;     for (; t < T_TOK; t += tstep) {
;       const float4 c0 = v0, c1 = v1, c2 = v2, c3 = v3;
;       const int tn = t + tstep < T_TOK ? t + tstep : t;
;       { const float4* xr = (const float4*)(x + (size_t)tn * 1024); v0 = xr[lane]; v1 = xr[lane + 64]; v2 = xr[lane + 128]; v3 = xr[lane + 192]; }
;       float ss = c0.x * c0.x + c0.y * c0.y + c0.z * c0.z + c0.w * c0.w + c1.x * c1.x + c1.y * c1.y + c1.z * c1.z + c1.w * c1.w
;                + c2.x * c2.x + c2.y * c2.y + c2.z * c2.z + c2.w * c2.w + c3.x * c3.x + c3.y * c3.y + c3.z * c3.z + c3.w * c3.w;
;       ss = wave_sum(ss);
;       const float r = rsqrtf(ss * (1.f / 1024.f) + 1e-6f);
;       bf16_t* hr = p.h + (size_t)t * 1024 + lane * 4;
;       uint2 o;
;       o.x = pack2(c0.x * r * gg[0].x, c0.y * r * gg[0].y); o.y = pack2(c0.z * r * gg[0].z, c0.w * r * gg[0].w); *(uint2*)(hr) = o;
;       o.x = pack2(c1.x * r * gg[1].x, c1.y * r * gg[1].y); o.y = pack2(c1.z * r * gg[1].z, c1.w * r * gg[1].w); *(uint2*)(hr + 256) = o;
;       o.x = pack2(c2.x * r * gg[2].x, c2.y * r * gg[2].y); o.y = pack2(c2.z * r * gg[2].z, c2.w * r * gg[2].w); *(uint2*)(hr + 512) = o;
;       o.x = pack2(c3.x * r * gg[3].x, c3.y * r * gg[3].y); o.y = pack2(c3.z * r * gg[3].z, c3.w * r * gg[3].w); *(uint2*)(hr + 768) = o;
;     }
.LBB0_2497:
	v_add_u32_e32 v35, s94, v34
	s_waitcnt vmcnt(3)
	v_pk_mul_f32 v[46:47], v[18:19], v[18:19]
	v_cmp_gt_i32_e64 s[0:1], s51, v35
	v_pk_mul_f32 v[48:49], v[20:21], v[20:21]
	v_add_f32_e32 v45, v47, v46
	v_cndmask_b32_e64 v46, v34, v35, s[0:1]
	v_cmp_lt_i32_e32 vcc, s46, v35
	v_mov_b32_e32 v34, v35
	v_add_f32_e32 v35, v48, v45
	v_ashrrev_i32_e32 v47, 31, v46
	s_waitcnt vmcnt(2)
	v_pk_mul_f32 v[50:51], v[22:23], v[22:23]
	v_add_f32_e32 v35, v49, v35
	v_lshlrev_b64 v[46:47], 12, v[46:47]
	v_add_f32_e32 v35, v35, v50
	v_lshl_add_u64 v[58:59], v[36:37], 0, v[46:47]
	v_add_f32_e32 v35, v51, v35
	global_load_dwordx4 v[46:49], v[58:59], off
	global_load_dwordx4 v[50:53], v[58:59], off offset:1024
	global_load_dwordx4 v[54:57], v[58:59], off offset:2048
	s_nop 0
	global_load_dwordx4 v[58:61], v[58:59], off offset:3072
	v_pk_mul_f32 v[62:63], v[24:25], v[24:25]
	s_waitcnt vmcnt(5)
	v_pk_mul_f32 v[64:65], v[26:27], v[26:27]
	v_add_f32_e32 v35, v62, v35
	v_add_f32_e32 v35, v63, v35
	v_add_f32_e32 v35, v64, v35
	v_pk_mul_f32 v[66:67], v[28:29], v[28:29]
	v_add_f32_e32 v35, v65, v35
	v_add_f32_e32 v35, v66, v35
	s_waitcnt vmcnt(4)
	v_pk_mul_f32 v[68:69], v[30:31], v[30:31]
	v_add_f32_e32 v35, v67, v35
	v_add_f32_e32 v35, v68, v35
	v_pk_mul_f32 v[70:71], v[32:33], v[32:33]
	v_add_f32_e32 v35, v69, v35
	v_add_f32_e32 v35, v70, v35
	v_add_f32_e32 v35, v71, v35
	s_or_b64 s[4:5], vcc, s[4:5]
	v_mov_b32_e32 v45, v35
	v_mov_b32_e32 v62, v35
	s_nop 1
	v_permlane32_swap_b32_e32 v45, v62
	v_add_f32_e32 v35, v45, v62
	ds_bpermute_b32 v45, v40, v35
	s_waitcnt lgkmcnt(0)
	v_add_f32_e32 v35, v35, v45
	s_nop 1
	v_add_f32_dpp v35, v35, v35 row_ror:8 row_mask:0xf bank_mask:0xf
	s_nop 1
	v_add_f32_dpp v35, v35, v35 row_ror:4 row_mask:0xf bank_mask:0xf
	s_nop 1
	v_add_f32_dpp v35, v35, v35 row_ror:2 row_mask:0xf bank_mask:0xf
	s_nop 1
	v_add_f32_dpp v35, v35, v35 row_ror:1 row_mask:0xf bank_mask:0xf
	v_fmamk_f32 v35, v35, 0x3a800000, v227
	v_mul_f32_e32 v45, 0x4b800000, v35
	v_cmp_gt_f32_e32 vcc, s6, v35
	s_nop 1
	v_cndmask_b32_e32 v35, v35, v45, vcc
	v_rsq_f32_e32 v35, v35
	s_nop 0
	v_mul_f32_e32 v45, 0x45800000, v35
	v_cndmask_b32_e32 v62, v35, v45, vcc
	v_pk_mul_f32 v[18:19], v[18:19], v[62:63] op_sel_hi:[1,0]
	v_pk_mul_f32 v[20:21], v[20:21], v[62:63] op_sel_hi:[1,0]
	v_pk_mul_f32 v[22:23], v[22:23], v[62:63] op_sel_hi:[1,0]
	v_pk_mul_f32 v[24:25], v[24:25], v[62:63] op_sel_hi:[1,0]
	v_pk_mul_f32 v[26:27], v[26:27], v[62:63] op_sel_hi:[1,0]
	v_pk_mul_f32 v[28:29], v[28:29], v[62:63] op_sel_hi:[1,0]
	v_pk_mul_f32 v[30:31], v[30:31], v[62:63] op_sel_hi:[1,0]
	v_pk_mul_f32 v[32:33], v[32:33], v[62:63] op_sel_hi:[1,0]
	v_pk_mul_f32 v[18:19], v[2:3], v[18:19]
	v_pk_mul_f32 v[20:21], v[4:5], v[20:21]
	v_pk_mul_f32 v[22:23], v[6:7], v[22:23]
	v_pk_mul_f32 v[24:25], v[8:9], v[24:25]
	v_pk_mul_f32 v[26:27], v[10:11], v[26:27]
	v_pk_mul_f32 v[28:29], v[12:13], v[28:29]
	v_pk_mul_f32 v[30:31], v[14:15], v[30:31]
	v_pk_mul_f32 v[32:33], v[16:17], v[32:33]
	v_cvt_pk_bf16_f32 v18, v18, v19
	v_cvt_pk_bf16_f32 v19, v20, v21
	v_cvt_pk_bf16_f32 v20, v22, v23
	v_cvt_pk_bf16_f32 v21, v24, v25
	v_cvt_pk_bf16_f32 v22, v26, v27
	v_cvt_pk_bf16_f32 v23, v28, v29
	v_cvt_pk_bf16_f32 v24, v30, v31
	v_cvt_pk_bf16_f32 v25, v32, v33
	global_store_dwordx2 v[38:39], v[18:19], off
	global_store_dwordx2 v[38:39], v[20:21], off offset:512
	global_store_dwordx2 v[38:39], v[22:23], off offset:1024
	global_store_dwordx2 v[38:39], v[24:25], off offset:1536
	v_lshl_add_u64 v[38:39], v[38:39], 0, s[44:45]
	s_waitcnt vmcnt(7)
	v_mov_b64_e32 v[20:21], v[48:49]
	v_mov_b64_e32 v[18:19], v[46:47]
	s_waitcnt vmcnt(6)
	v_mov_b64_e32 v[24:25], v[52:53]
	v_mov_b64_e32 v[22:23], v[50:51]
	s_waitcnt vmcnt(5)
	v_mov_b64_e32 v[28:29], v[56:57]
	v_mov_b64_e32 v[26:27], v[54:55]
	s_waitcnt vmcnt(4)
	v_mov_b64_e32 v[30:31], v[58:59]
	v_mov_b64_e32 v[32:33], v[60:61]
	s_andn2_b64 exec, exec, s[4:5]
	s_cbranch_execnz .LBB0_2497
